# stack11 plus nt (streaming) hint on the P0 weight-conversion stores (int8 gate/up strips and bf16 conversion jobs)
# speedup vs baseline: 1.0108x; 1.0108x over previous
.LBB0_16:
	s_or_b64 exec, exec, s[8:9]
	v_div_scale_f32 v153, s[8:9], v9, v9, s22
	v_rcp_f32_e32 v154, v153
	s_mul_hi_i32 s29, s27, 0x1600000
	s_mul_i32 s27, s27, 0x1600000
	s_add_u32 s8, s10, s27
	v_fma_f32 v155, -v153, v154, 1.0
	v_fmac_f32_e32 v154, v155, v154
	v_div_scale_f32 v155, vcc, s22, v9, s22
	v_mul_f32_e32 v156, v155, v154
	v_fma_f32 v157, -v153, v156, v155
	v_fmac_f32_e32 v156, v157, v154
	v_fma_f32 v153, -v153, v156, v155
	v_div_fmas_f32 v153, v153, v154, v156
	v_div_fixup_f32 v9, v153, v9, s22
	v_cndmask_b32_e64 v9, 0, v9, s[6:7]
	v_fmaak_f32 v26, v26, v9, 0x4b400000
	v_fmaak_f32 v27, v27, v9, 0x4b400000
	v_fmaak_f32 v28, v28, v9, 0x4b400000
	v_perm_b32 v26, v27, v26, s23
	v_fmaak_f32 v29, v29, v9, 0x4b400000
	v_perm_b32 v26, v28, v26, s24
	v_fmaak_f32 v27, v30, v9, 0x4b400000
	v_fmaak_f32 v28, v31, v9, 0x4b400000
	v_perm_b32 v26, v29, v26, s25
	v_fmaak_f32 v29, v32, v9, 0x4b400000
	v_perm_b32 v27, v28, v27, s23
	v_fmaak_f32 v30, v33, v9, 0x4b400000
	v_perm_b32 v27, v29, v27, s24
	v_perm_b32 v27, v30, v27, s25
	v_add_u32_e32 v28, 0x800, v11
	ds_write2_b32 v28, v26, v27 offset1:16
	v_fmaak_f32 v26, v34, v9, 0x4b400000
	v_fmaak_f32 v27, v35, v9, 0x4b400000
	v_fmaak_f32 v29, v36, v9, 0x4b400000
	v_perm_b32 v26, v27, v26, s23
	v_fmaak_f32 v30, v37, v9, 0x4b400000
	v_perm_b32 v26, v29, v26, s24
	v_fmaak_f32 v27, v38, v9, 0x4b400000
	v_fmaak_f32 v29, v39, v9, 0x4b400000
	v_perm_b32 v26, v30, v26, s25
	v_fmaak_f32 v30, v40, v9, 0x4b400000
	v_perm_b32 v27, v29, v27, s23
	v_fmaak_f32 v31, v41, v9, 0x4b400000
	v_perm_b32 v27, v30, v27, s24
	v_perm_b32 v27, v31, v27, s25
	ds_write2_b32 v28, v26, v27 offset0:32 offset1:48
	v_fmaak_f32 v26, v42, v9, 0x4b400000
	v_fmaak_f32 v27, v43, v9, 0x4b400000
	v_fmaak_f32 v29, v44, v9, 0x4b400000
	v_perm_b32 v26, v27, v26, s23
	v_fmaak_f32 v30, v45, v9, 0x4b400000
	v_perm_b32 v26, v29, v26, s24
	v_fmaak_f32 v27, v46, v9, 0x4b400000
	v_fmaak_f32 v29, v47, v9, 0x4b400000
	v_perm_b32 v26, v30, v26, s25
	v_fmaak_f32 v30, v48, v9, 0x4b400000
	v_perm_b32 v27, v29, v27, s23
	v_fmaak_f32 v31, v49, v9, 0x4b400000
	v_perm_b32 v27, v30, v27, s24
	v_perm_b32 v27, v31, v27, s25
	ds_write2_b32 v28, v26, v27 offset0:64 offset1:80
	v_fmaak_f32 v26, v50, v9, 0x4b400000
	v_fmaak_f32 v27, v51, v9, 0x4b400000
	v_fmaak_f32 v29, v52, v9, 0x4b400000
	v_perm_b32 v26, v27, v26, s23
	v_fmaak_f32 v30, v53, v9, 0x4b400000
	v_perm_b32 v26, v29, v26, s24
	v_fmaak_f32 v27, v54, v9, 0x4b400000
	v_fmaak_f32 v29, v55, v9, 0x4b400000
	v_perm_b32 v26, v30, v26, s25
	v_fmaak_f32 v30, v56, v9, 0x4b400000
	v_perm_b32 v27, v29, v27, s23
	v_fmaak_f32 v31, v57, v9, 0x4b400000
	v_perm_b32 v27, v30, v27, s24
	v_perm_b32 v27, v31, v27, s25
	ds_write2_b32 v28, v26, v27 offset0:96 offset1:112
	v_fmaak_f32 v26, v58, v9, 0x4b400000
	v_fmaak_f32 v27, v59, v9, 0x4b400000
	v_fmaak_f32 v29, v60, v9, 0x4b400000
	v_perm_b32 v26, v27, v26, s23
	v_fmaak_f32 v30, v61, v9, 0x4b400000
	v_perm_b32 v26, v29, v26, s24
	v_fmaak_f32 v27, v62, v9, 0x4b400000
	v_fmaak_f32 v29, v63, v9, 0x4b400000
	v_perm_b32 v26, v30, v26, s25
	v_fmaak_f32 v30, v64, v9, 0x4b400000
	v_perm_b32 v27, v29, v27, s23
	v_fmaak_f32 v31, v65, v9, 0x4b400000
	v_perm_b32 v27, v30, v27, s24
	v_perm_b32 v27, v31, v27, s25
	ds_write2_b32 v28, v26, v27 offset0:128 offset1:144
	v_fmaak_f32 v26, v66, v9, 0x4b400000
	v_fmaak_f32 v27, v67, v9, 0x4b400000
	v_fmaak_f32 v29, v68, v9, 0x4b400000
	v_perm_b32 v26, v27, v26, s23
	v_fmaak_f32 v30, v69, v9, 0x4b400000
	v_perm_b32 v26, v29, v26, s24
	v_fmaak_f32 v27, v70, v9, 0x4b400000
	v_fmaak_f32 v29, v71, v9, 0x4b400000
	v_perm_b32 v26, v30, v26, s25
	v_fmaak_f32 v30, v72, v9, 0x4b400000
	v_perm_b32 v27, v29, v27, s23
	v_fmaak_f32 v31, v73, v9, 0x4b400000
	v_perm_b32 v27, v30, v27, s24
	v_perm_b32 v27, v31, v27, s25
	ds_write2_b32 v28, v26, v27 offset0:160 offset1:176
	v_fmaak_f32 v26, v74, v9, 0x4b400000
	v_fmaak_f32 v27, v75, v9, 0x4b400000
	v_fmaak_f32 v29, v76, v9, 0x4b400000
	v_perm_b32 v26, v27, v26, s23
	v_fmaak_f32 v30, v77, v9, 0x4b400000
	v_perm_b32 v26, v29, v26, s24
	v_fmaak_f32 v27, v78, v9, 0x4b400000
	v_fmaak_f32 v29, v79, v9, 0x4b400000
	v_perm_b32 v26, v30, v26, s25
	v_fmaak_f32 v30, v80, v9, 0x4b400000
	v_perm_b32 v27, v29, v27, s23
	v_fmaak_f32 v31, v81, v9, 0x4b400000
	v_perm_b32 v27, v30, v27, s24
	v_perm_b32 v27, v31, v27, s25
	ds_write2_b32 v28, v26, v27 offset0:192 offset1:208
	v_fmaak_f32 v26, v82, v9, 0x4b400000
	v_fmaak_f32 v27, v83, v9, 0x4b400000
	v_fmaak_f32 v29, v84, v9, 0x4b400000
	v_perm_b32 v26, v27, v26, s23
	v_fmaak_f32 v30, v85, v9, 0x4b400000
	v_perm_b32 v26, v29, v26, s24
	v_fmaak_f32 v27, v86, v9, 0x4b400000
	v_fmaak_f32 v29, v87, v9, 0x4b400000
	v_perm_b32 v26, v30, v26, s25
	v_fmaak_f32 v30, v88, v9, 0x4b400000
	v_perm_b32 v27, v29, v27, s23
	v_fmaak_f32 v31, v89, v9, 0x4b400000
	v_perm_b32 v27, v30, v27, s24
	v_perm_b32 v27, v31, v27, s25
	ds_write2_b32 v28, v26, v27 offset0:224 offset1:240
	v_fmaak_f32 v26, v90, v9, 0x4b400000
	v_fmaak_f32 v27, v91, v9, 0x4b400000
	v_fmaak_f32 v28, v92, v9, 0x4b400000
	v_perm_b32 v26, v27, v26, s23
	v_fmaak_f32 v29, v93, v9, 0x4b400000
	v_perm_b32 v26, v28, v26, s24
	v_fmaak_f32 v27, v94, v9, 0x4b400000
	v_fmaak_f32 v28, v95, v9, 0x4b400000
	v_perm_b32 v26, v29, v26, s25
	v_fmaak_f32 v29, v96, v9, 0x4b400000
	v_perm_b32 v27, v28, v27, s23
	v_fmaak_f32 v30, v97, v9, 0x4b400000
	v_perm_b32 v27, v29, v27, s24
	v_perm_b32 v27, v30, v27, s25
	v_add_u32_e32 v28, 0xc00, v11
	ds_write2_b32 v28, v26, v27 offset1:16
	v_fmaak_f32 v26, v98, v9, 0x4b400000
	v_fmaak_f32 v27, v99, v9, 0x4b400000
	v_fmaak_f32 v29, v100, v9, 0x4b400000
	v_perm_b32 v26, v27, v26, s23
	v_fmaak_f32 v30, v101, v9, 0x4b400000
	v_perm_b32 v26, v29, v26, s24
	v_fmaak_f32 v27, v102, v9, 0x4b400000
	v_fmaak_f32 v29, v103, v9, 0x4b400000
	v_perm_b32 v26, v30, v26, s25
	v_fmaak_f32 v30, v104, v9, 0x4b400000
	v_perm_b32 v27, v29, v27, s23
	v_fmaak_f32 v31, v105, v9, 0x4b400000
	v_perm_b32 v27, v30, v27, s24
	v_perm_b32 v27, v31, v27, s25
	ds_write2_b32 v28, v26, v27 offset0:32 offset1:48
	v_fmaak_f32 v26, v106, v9, 0x4b400000
	v_fmaak_f32 v27, v107, v9, 0x4b400000
	v_fmaak_f32 v29, v108, v9, 0x4b400000
	v_perm_b32 v26, v27, v26, s23
	v_fmaak_f32 v30, v109, v9, 0x4b400000
	v_perm_b32 v26, v29, v26, s24
	v_fmaak_f32 v27, v110, v9, 0x4b400000
	v_fmaak_f32 v29, v111, v9, 0x4b400000
	v_perm_b32 v26, v30, v26, s25
	v_fmaak_f32 v30, v112, v9, 0x4b400000
	v_perm_b32 v27, v29, v27, s23
	v_fmaak_f32 v31, v113, v9, 0x4b400000
	v_perm_b32 v27, v30, v27, s24
	v_perm_b32 v27, v31, v27, s25
	ds_write2_b32 v28, v26, v27 offset0:64 offset1:80
	v_fmaak_f32 v26, v114, v9, 0x4b400000
	v_fmaak_f32 v27, v115, v9, 0x4b400000
	v_fmaak_f32 v29, v116, v9, 0x4b400000
	v_perm_b32 v26, v27, v26, s23
	v_fmaak_f32 v30, v117, v9, 0x4b400000
	v_perm_b32 v26, v29, v26, s24
	v_fmaak_f32 v27, v118, v9, 0x4b400000
	v_fmaak_f32 v29, v119, v9, 0x4b400000
	v_perm_b32 v26, v30, v26, s25
	v_fmaak_f32 v30, v120, v9, 0x4b400000
	v_perm_b32 v27, v29, v27, s23
	v_fmaak_f32 v31, v121, v9, 0x4b400000
	v_perm_b32 v27, v30, v27, s24
	v_perm_b32 v27, v31, v27, s25
	ds_write2_b32 v28, v26, v27 offset0:96 offset1:112
	v_fmaak_f32 v26, v122, v9, 0x4b400000
	v_fmaak_f32 v27, v123, v9, 0x4b400000
	v_fmaak_f32 v29, v124, v9, 0x4b400000
	v_perm_b32 v26, v27, v26, s23
	v_fmaak_f32 v30, v125, v9, 0x4b400000
	v_perm_b32 v26, v29, v26, s24
	v_fmaak_f32 v27, v126, v9, 0x4b400000
	v_fmaak_f32 v29, v127, v9, 0x4b400000
	v_perm_b32 v26, v30, v26, s25
	v_fmaak_f32 v30, v128, v9, 0x4b400000
	v_perm_b32 v27, v29, v27, s23
	v_fmaak_f32 v31, v129, v9, 0x4b400000
	v_perm_b32 v27, v30, v27, s24
	v_perm_b32 v27, v31, v27, s25
	ds_write2_b32 v28, v26, v27 offset0:128 offset1:144
	v_fmaak_f32 v26, v130, v9, 0x4b400000
	v_fmaak_f32 v27, v131, v9, 0x4b400000
	v_fmaak_f32 v29, v132, v9, 0x4b400000
	v_perm_b32 v26, v27, v26, s23
	v_fmaak_f32 v30, v133, v9, 0x4b400000
	v_perm_b32 v26, v29, v26, s24
	v_fmaak_f32 v27, v134, v9, 0x4b400000
	v_fmaak_f32 v29, v135, v9, 0x4b400000
	v_perm_b32 v26, v30, v26, s25
	v_fmaak_f32 v30, v136, v9, 0x4b400000
	v_perm_b32 v27, v29, v27, s23
	v_fmaak_f32 v31, v137, v9, 0x4b400000
	v_perm_b32 v27, v30, v27, s24
	v_perm_b32 v27, v31, v27, s25
	ds_write2_b32 v28, v26, v27 offset0:160 offset1:176
	v_fmaak_f32 v26, v138, v9, 0x4b400000
	v_fmaak_f32 v27, v139, v9, 0x4b400000
	v_fmaak_f32 v29, v140, v9, 0x4b400000
	v_perm_b32 v26, v27, v26, s23
	v_fmaak_f32 v30, v141, v9, 0x4b400000
	v_perm_b32 v26, v29, v26, s24
	v_fmaak_f32 v27, v142, v9, 0x4b400000
	v_fmaak_f32 v29, v143, v9, 0x4b400000
	v_perm_b32 v26, v30, v26, s25
	v_fmaak_f32 v30, v144, v9, 0x4b400000
	v_perm_b32 v27, v29, v27, s23
	v_fmaak_f32 v31, v145, v9, 0x4b400000
	v_perm_b32 v27, v30, v27, s24
	v_perm_b32 v27, v31, v27, s25
	ds_write2_b32 v28, v26, v27 offset0:192 offset1:208
	v_fmaak_f32 v26, v146, v9, 0x4b400000
	v_fmaak_f32 v27, v147, v9, 0x4b400000
	v_fmaak_f32 v29, v148, v9, 0x4b400000
	v_perm_b32 v26, v27, v26, s23
	v_fmaak_f32 v30, v149, v9, 0x4b400000
	v_perm_b32 v26, v29, v26, s24
	v_fmaak_f32 v27, v150, v9, 0x4b400000
	v_fmaak_f32 v29, v151, v9, 0x4b400000
	v_perm_b32 v26, v30, v26, s25
	v_fmaak_f32 v30, v152, v9, 0x4b400000
	v_fmaak_f32 v8, v8, v9, 0x4b400000
	v_perm_b32 v9, v29, v27, s23
	v_perm_b32 v9, v30, v9, s24
	v_perm_b32 v8, v8, v9, s25
	ds_write2_b32 v28, v26, v8 offset0:224 offset1:240
	v_add_u32_e32 v8, 0x800, v20
	s_waitcnt lgkmcnt(0)
	s_barrier
	v_add_u32_e32 v9, 0x808, v20
	ds_read2_b32 v[26:27], v8 offset1:1
	ds_read2_b32 v[28:29], v9 offset1:1
	v_or_b32_e32 v8, s28, v12
	v_ashrrev_i32_e32 v9, 31, v8
	s_addc_u32 s9, s11, s29
	v_lshlrev_b64 v[8:9], 11, v[8:9]
	v_lshl_add_u64 v[8:9], s[8:9], 0, v[8:9]
	v_lshl_add_u64 v[8:9], v[8:9], 0, v[4:5]
	v_add_u32_e32 v30, 0x800, v21
	v_add_u32_e32 v32, 0x808, v21
	ds_read2_b32 v[30:31], v30 offset1:1
	ds_read2_b32 v[32:33], v32 offset1:1
	s_waitcnt lgkmcnt(2)
	global_store_dwordx4 v[8:9], v[26:29], off nt
	v_or_b32_e32 v8, s28, v13
	v_ashrrev_i32_e32 v9, 31, v8
	v_lshlrev_b64 v[8:9], 11, v[8:9]
	v_lshl_add_u64 v[8:9], s[8:9], 0, v[8:9]
	v_lshl_add_u64 v[8:9], v[8:9], 0, v[4:5]
	s_waitcnt lgkmcnt(0)
	global_store_dwordx4 v[8:9], v[30:33], off nt
	v_add_u32_e32 v8, 0x4820, v20
	v_add_u32_e32 v9, 0x4828, v20
	ds_read2_b32 v[26:27], v8 offset1:1
	ds_read2_b32 v[28:29], v9 offset1:1
	v_or_b32_e32 v8, s28, v14
	v_ashrrev_i32_e32 v9, 31, v8
	v_lshlrev_b64 v[8:9], 11, v[8:9]
	v_lshl_add_u64 v[8:9], s[8:9], 0, v[8:9]
	v_lshl_add_u64 v[8:9], v[8:9], 0, v[4:5]
	v_add_u32_e32 v30, 0x800, v22
	v_add_u32_e32 v32, 0x808, v22
	ds_read2_b32 v[30:31], v30 offset1:1
	ds_read2_b32 v[32:33], v32 offset1:1
	s_waitcnt lgkmcnt(2)
	global_store_dwordx4 v[8:9], v[26:29], off nt
	v_or_b32_e32 v8, s28, v15
	v_ashrrev_i32_e32 v9, 31, v8
	v_lshlrev_b64 v[8:9], 11, v[8:9]
	v_lshl_add_u64 v[8:9], s[8:9], 0, v[8:9]
	v_lshl_add_u64 v[8:9], v[8:9], 0, v[4:5]
	s_waitcnt lgkmcnt(0)
	global_store_dwordx4 v[8:9], v[30:33], off nt
	v_add_u32_e32 v8, 0x8840, v20
	v_add_u32_e32 v9, 0x8848, v20
	ds_read2_b32 v[26:27], v8 offset1:1
	ds_read2_b32 v[28:29], v9 offset1:1
	v_or_b32_e32 v8, s28, v16
	v_ashrrev_i32_e32 v9, 31, v8
	v_lshlrev_b64 v[8:9], 11, v[8:9]
	v_lshl_add_u64 v[8:9], s[8:9], 0, v[8:9]
	v_lshl_add_u64 v[8:9], v[8:9], 0, v[4:5]
	v_add_u32_e32 v30, 0x800, v23
	v_add_u32_e32 v32, 0x808, v23
	ds_read2_b32 v[30:31], v30 offset1:1
	ds_read2_b32 v[32:33], v32 offset1:1
	s_waitcnt lgkmcnt(2)
	global_store_dwordx4 v[8:9], v[26:29], off nt
	v_or_b32_e32 v8, s28, v17
	v_ashrrev_i32_e32 v9, 31, v8
	v_lshlrev_b64 v[8:9], 11, v[8:9]
	v_lshl_add_u64 v[8:9], s[8:9], 0, v[8:9]
	v_lshl_add_u64 v[8:9], v[8:9], 0, v[4:5]
	s_waitcnt lgkmcnt(0)
	global_store_dwordx4 v[8:9], v[30:33], off nt
	v_add_u32_e32 v8, 0xc860, v20
	v_add_u32_e32 v9, 0xc868, v20
	ds_read2_b32 v[26:27], v8 offset1:1
	ds_read2_b32 v[28:29], v9 offset1:1
	v_or_b32_e32 v8, s28, v18
	v_ashrrev_i32_e32 v9, 31, v8
	v_lshlrev_b64 v[8:9], 11, v[8:9]
	v_lshl_add_u64 v[8:9], s[8:9], 0, v[8:9]
	v_lshl_add_u64 v[8:9], v[8:9], 0, v[4:5]
	v_add_u32_e32 v30, 0x800, v24
	v_add_u32_e32 v32, 0x808, v24
	ds_read2_b32 v[30:31], v30 offset1:1
	ds_read2_b32 v[32:33], v32 offset1:1
	s_waitcnt lgkmcnt(2)
	global_store_dwordx4 v[8:9], v[26:29], off nt
	v_add_u32_e32 v8, s28, v19
	v_ashrrev_i32_e32 v9, 31, v8
	v_lshlrev_b64 v[8:9], 11, v[8:9]
	v_lshl_add_u64 v[8:9], s[8:9], 0, v[8:9]
	s_add_i32 s26, s26, s90
	s_add_i32 s14, s14, s15
	v_lshl_add_u64 v[8:9], v[8:9], 0, v[4:5]
	s_cmpk_lt_i32 s26, 0xb00
	s_waitcnt lgkmcnt(0)
	global_store_dwordx4 v[8:9], v[30:33], off nt
	s_barrier
	s_cbranch_scc0 .LBB0_19

.LBB0_21:
	s_mul_hi_i32 s8, s7, 0x66666667
	s_lshr_b32 s9, s8, 31
	s_ashr_i32 s8, s8, 5
	s_add_i32 s8, s8, s9
	s_mul_i32 s9, s8, 0xfffff600
	s_lshl_b32 s8, s8, 6
	s_add_i32 s10, s4, s9
	v_or_b32_e32 v26, s8, v1
	s_ashr_i32 s11, s10, 31
	v_or_b32_e32 v28, 8, v26
	v_or_b32_e32 v30, 16, v26
	v_or_b32_e32 v31, 24, v26
	v_or_b32_e32 v34, 32, v26
	v_or_b32_e32 v35, 40, v26
	v_or_b32_e32 v38, 48, v26
	v_or_b32_e32 v39, 56, v26
	v_lshl_add_u64 v[24:25], s[10:11], 2, v[6:7]
	v_mad_i64_i32 v[26:27], s[12:13], v26, s6, v[24:25]
	v_mad_i64_i32 v[28:29], s[12:13], v28, s6, v[24:25]
	v_mad_i64_i32 v[32:33], s[12:13], v30, s6, v[24:25]
	v_mad_i64_i32 v[36:37], s[12:13], v31, s6, v[24:25]
	v_mad_i64_i32 v[40:41], s[12:13], v34, s6, v[24:25]
	v_mad_i64_i32 v[44:45], s[12:13], v35, s6, v[24:25]
	v_mad_i64_i32 v[48:49], s[12:13], v38, s6, v[24:25]
	v_mad_i64_i32 v[52:53], s[12:13], v39, s6, v[24:25]
	global_load_dwordx4 v[24:27], v[26:27], off nt
	s_nop 0
	global_load_dwordx4 v[28:31], v[28:29], off nt
	s_nop 0
	global_load_dwordx4 v[32:35], v[32:33], off nt
	s_nop 0
	global_load_dwordx4 v[36:39], v[36:37], off nt
	s_nop 0
	global_load_dwordx4 v[40:43], v[40:41], off nt
	s_nop 0
	global_load_dwordx4 v[44:47], v[44:45], off nt
	s_nop 0
	global_load_dwordx4 v[48:51], v[48:49], off nt
	s_nop 0
	global_load_dwordx4 v[52:55], v[52:53], off nt
	v_add_u32_e32 v58, s10, v1
	s_ashr_i32 s9, s8, 31
	v_ashrrev_i32_e32 v59, 31, v58
	v_lshl_add_u64 v[56:57], s[8:9], 1, v[8:9]
	v_lshlrev_b64 v[64:65], 12, v[58:59]
	v_add_u32_e32 v60, 8, v58
	v_lshl_add_u64 v[64:65], v[56:57], 0, v[64:65]
	v_ashrrev_i32_e32 v61, 31, v60
	v_lshlrev_b64 v[60:61], 12, v[60:61]
	v_add_u32_e32 v62, 16, v58
	v_lshl_add_u64 v[60:61], v[56:57], 0, v[60:61]
	v_ashrrev_i32_e32 v63, 31, v62
	v_lshlrev_b64 v[62:63], 12, v[62:63]
	v_lshl_add_u64 v[62:63], v[56:57], 0, v[62:63]
	s_add_i32 s7, s7, s28
	s_add_i32 s4, s4, s5
	s_cmpk_lt_i32 s7, 0xa00
	s_waitcnt vmcnt(7)
	ds_write2_b32 v11, v24, v25 offset1:1
	ds_write2_b32 v11, v26, v27 offset0:2 offset1:3
	s_waitcnt vmcnt(6)
	ds_write2_b32 v3, v28, v29 offset1:1
	ds_write2_b32 v5, v30, v31 offset1:1
	s_waitcnt vmcnt(5)
	ds_write2_b32 v12, v32, v33 offset1:1
	ds_write2_b32 v13, v34, v35 offset1:1
	s_waitcnt vmcnt(4)
	ds_write2_b32 v14, v36, v37 offset1:1
	ds_write2_b32 v15, v38, v39 offset1:1
	s_waitcnt vmcnt(3)
	ds_write2_b32 v16, v40, v41 offset1:1
	ds_write2_b32 v17, v42, v43 offset1:1
	s_waitcnt vmcnt(2)
	ds_write2_b32 v18, v44, v45 offset1:1
	ds_write2_b32 v19, v46, v47 offset1:1
	s_waitcnt vmcnt(1)
	ds_write2_b32 v20, v48, v49 offset1:1
	ds_write2_b32 v21, v50, v51 offset1:1
	s_waitcnt vmcnt(0)
	ds_write2_b32 v22, v52, v53 offset1:1
	ds_write2_b32 v23, v54, v55 offset1:1
	s_waitcnt lgkmcnt(0)
	ds_read2_b32 v[24:25], v10 offset1:33
	s_waitcnt lgkmcnt(0)
	v_cvt_pk_bf16_f32 v24, v24, v25
	ds_read2_b32 v[26:27], v10 offset0:66 offset1:99
	s_waitcnt lgkmcnt(0)
	v_cvt_pk_bf16_f32 v25, v26, v27
	ds_read2_b32 v[26:27], v10 offset0:132 offset1:165
	s_waitcnt lgkmcnt(0)
	v_cvt_pk_bf16_f32 v26, v26, v27
	ds_read2_b32 v[28:29], v10 offset0:198 offset1:231
	s_waitcnt lgkmcnt(0)
	v_cvt_pk_bf16_f32 v27, v28, v29
	ds_read2_b32 v[28:29], v10 offset0:8 offset1:41
	global_store_dwordx4 v[64:65], v[24:27], off nt
	v_add_u32_e32 v30, 24, v58
	v_ashrrev_i32_e32 v31, 31, v30
	s_waitcnt lgkmcnt(0)
	v_cvt_pk_bf16_f32 v24, v28, v29
	ds_read2_b32 v[26:27], v10 offset0:74 offset1:107
	s_waitcnt lgkmcnt(0)
	v_cvt_pk_bf16_f32 v25, v26, v27
	ds_read2_b32 v[26:27], v10 offset0:140 offset1:173
	s_waitcnt lgkmcnt(0)
	v_cvt_pk_bf16_f32 v26, v26, v27
	ds_read2_b32 v[28:29], v10 offset0:206 offset1:239
	s_waitcnt lgkmcnt(0)
	v_cvt_pk_bf16_f32 v27, v28, v29
	ds_read2_b32 v[28:29], v10 offset0:16 offset1:49
	global_store_dwordx4 v[60:61], v[24:27], off nt
	v_lshlrev_b64 v[30:31], 12, v[30:31]
	v_lshl_add_u64 v[30:31], v[56:57], 0, v[30:31]
	s_waitcnt lgkmcnt(0)
	v_cvt_pk_bf16_f32 v24, v28, v29
	ds_read2_b32 v[26:27], v10 offset0:82 offset1:115
	s_waitcnt lgkmcnt(0)
	v_cvt_pk_bf16_f32 v25, v26, v27
	ds_read2_b32 v[26:27], v10 offset0:148 offset1:181
	s_waitcnt lgkmcnt(0)
	v_cvt_pk_bf16_f32 v26, v26, v27
	ds_read2_b32 v[28:29], v10 offset0:214 offset1:247
	s_waitcnt lgkmcnt(0)
	v_cvt_pk_bf16_f32 v27, v28, v29
	ds_read2_b32 v[28:29], v10 offset0:24 offset1:57
	global_store_dwordx4 v[62:63], v[24:27], off nt
	s_waitcnt lgkmcnt(0)
	s_nop 0
	v_cvt_pk_bf16_f32 v24, v28, v29
	ds_read2_b32 v[26:27], v10 offset0:90 offset1:123
	s_waitcnt lgkmcnt(0)
	v_cvt_pk_bf16_f32 v25, v26, v27
	ds_read2_b32 v[26:27], v10 offset0:156 offset1:189
	s_waitcnt lgkmcnt(0)
	v_cvt_pk_bf16_f32 v26, v26, v27
	ds_read2_b32 v[28:29], v10 offset0:222 offset1:255
	s_waitcnt lgkmcnt(0)
	v_cvt_pk_bf16_f32 v27, v28, v29
	global_store_dwordx4 v[30:31], v[24:27], off nt
	s_waitcnt lgkmcnt(0)
	s_cbranch_scc1 .LBB0_21

.LBB0_24:
	s_ashr_i32 s6, s12, 31
	s_lshr_b32 s6, s6, 26
	s_add_i32 s6, s12, s6
	s_lshl_b32 s7, s6, 5
	s_and_b32 s8, s6, 0xffffffc0
	s_and_b32 s6, s7, 0xfffff800
	v_or_b32_e32 v24, s8, v1
	s_sub_i32 s6, s10, s6
	v_or_b32_e32 v26, 8, v24
	v_or_b32_e32 v28, 16, v24
	v_or_b32_e32 v30, 24, v24
	v_or_b32_e32 v32, 32, v24
	v_or_b32_e32 v34, 40, v24
	v_or_b32_e32 v36, 48, v24
	v_or_b32_e32 v38, 56, v24
	v_ashrrev_i32_e32 v25, 31, v24
	s_ashr_i32 s7, s6, 31
	v_ashrrev_i32_e32 v27, 31, v26
	v_ashrrev_i32_e32 v29, 31, v28
	v_ashrrev_i32_e32 v31, 31, v30
	v_ashrrev_i32_e32 v33, 31, v32
	v_ashrrev_i32_e32 v35, 31, v34
	v_ashrrev_i32_e32 v37, 31, v36
	v_ashrrev_i32_e32 v39, 31, v38
	v_lshlrev_b64 v[24:25], 13, v[24:25]
	v_lshl_add_u64 v[40:41], s[6:7], 2, v[6:7]
	v_lshlrev_b64 v[26:27], 13, v[26:27]
	v_lshlrev_b64 v[28:29], 13, v[28:29]
	v_lshlrev_b64 v[30:31], 13, v[30:31]
	v_lshlrev_b64 v[32:33], 13, v[32:33]
	v_lshlrev_b64 v[34:35], 13, v[34:35]
	v_lshlrev_b64 v[36:37], 13, v[36:37]
	v_lshlrev_b64 v[38:39], 13, v[38:39]
	v_lshl_add_u64 v[24:25], v[40:41], 0, v[24:25]
	v_lshl_add_u64 v[42:43], v[40:41], 0, v[26:27]
	v_lshl_add_u64 v[44:45], v[40:41], 0, v[28:29]
	v_lshl_add_u64 v[46:47], v[40:41], 0, v[30:31]
	v_lshl_add_u64 v[48:49], v[40:41], 0, v[32:33]
	v_lshl_add_u64 v[50:51], v[40:41], 0, v[34:35]
	v_lshl_add_u64 v[52:53], v[40:41], 0, v[36:37]
	v_lshl_add_u64 v[54:55], v[40:41], 0, v[38:39]
	global_load_dwordx4 v[24:27], v[24:25], off nt
	s_nop 0
	global_load_dwordx4 v[28:31], v[42:43], off nt
	global_load_dwordx4 v[32:35], v[44:45], off nt
	global_load_dwordx4 v[36:39], v[46:47], off nt
	s_nop 0
	global_load_dwordx4 v[40:43], v[48:49], off nt
	global_load_dwordx4 v[44:47], v[50:51], off nt
	s_nop 0
	global_load_dwordx4 v[48:51], v[52:53], off nt
	s_nop 0
	global_load_dwordx4 v[52:55], v[54:55], off nt
	v_add_u32_e32 v58, s6, v1
	s_ashr_i32 s9, s8, 31
	v_ashrrev_i32_e32 v59, 31, v58
	v_lshl_add_u64 v[56:57], s[8:9], 1, v[8:9]
	v_lshlrev_b64 v[64:65], 12, v[58:59]
	v_add_u32_e32 v60, 8, v58
	v_lshl_add_u64 v[64:65], v[56:57], 0, v[64:65]
	v_ashrrev_i32_e32 v61, 31, v60
	v_lshlrev_b64 v[60:61], 12, v[60:61]
	v_add_u32_e32 v62, 16, v58
	v_lshl_add_u64 v[60:61], v[56:57], 0, v[60:61]
	v_ashrrev_i32_e32 v63, 31, v62
	v_lshlrev_b64 v[62:63], 12, v[62:63]
	v_lshl_add_u64 v[62:63], v[56:57], 0, v[62:63]
	s_add_i32 s12, s12, s28
	s_add_i32 s10, s10, s11
	s_cmpk_lt_i32 s12, 0x800
	s_waitcnt vmcnt(7)
	ds_write2_b32 v11, v24, v25 offset1:1
	ds_write2_b32 v11, v26, v27 offset0:2 offset1:3
	s_waitcnt vmcnt(6)
	ds_write2_b32 v3, v28, v29 offset1:1
	ds_write2_b32 v5, v30, v31 offset1:1
	s_waitcnt vmcnt(5)
	ds_write2_b32 v12, v32, v33 offset1:1
	ds_write2_b32 v13, v34, v35 offset1:1
	s_waitcnt vmcnt(4)
	ds_write2_b32 v14, v36, v37 offset1:1
	ds_write2_b32 v15, v38, v39 offset1:1
	s_waitcnt vmcnt(3)
	ds_write2_b32 v16, v40, v41 offset1:1
	ds_write2_b32 v17, v42, v43 offset1:1
	s_waitcnt vmcnt(2)
	ds_write2_b32 v18, v44, v45 offset1:1
	ds_write2_b32 v19, v46, v47 offset1:1
	s_waitcnt vmcnt(1)
	ds_write2_b32 v20, v48, v49 offset1:1
	ds_write2_b32 v21, v50, v51 offset1:1
	s_waitcnt vmcnt(0)
	ds_write2_b32 v22, v52, v53 offset1:1
	ds_write2_b32 v23, v54, v55 offset1:1
	s_waitcnt lgkmcnt(0)
	ds_read2_b32 v[24:25], v10 offset1:33
	s_waitcnt lgkmcnt(0)
	v_cvt_pk_bf16_f32 v24, v24, v25
	ds_read2_b32 v[26:27], v10 offset0:66 offset1:99
	s_waitcnt lgkmcnt(0)
	v_cvt_pk_bf16_f32 v25, v26, v27
	ds_read2_b32 v[26:27], v10 offset0:132 offset1:165
	s_waitcnt lgkmcnt(0)
	v_cvt_pk_bf16_f32 v26, v26, v27
	ds_read2_b32 v[28:29], v10 offset0:198 offset1:231
	s_waitcnt lgkmcnt(0)
	v_cvt_pk_bf16_f32 v27, v28, v29
	ds_read2_b32 v[28:29], v10 offset0:8 offset1:41
	global_store_dwordx4 v[64:65], v[24:27], off nt
	v_add_u32_e32 v30, 24, v58
	v_ashrrev_i32_e32 v31, 31, v30
	s_waitcnt lgkmcnt(0)
	v_cvt_pk_bf16_f32 v24, v28, v29
	ds_read2_b32 v[26:27], v10 offset0:74 offset1:107
	s_waitcnt lgkmcnt(0)
	v_cvt_pk_bf16_f32 v25, v26, v27
	ds_read2_b32 v[26:27], v10 offset0:140 offset1:173
	s_waitcnt lgkmcnt(0)
	v_cvt_pk_bf16_f32 v26, v26, v27
	ds_read2_b32 v[28:29], v10 offset0:206 offset1:239
	s_waitcnt lgkmcnt(0)
	v_cvt_pk_bf16_f32 v27, v28, v29
	ds_read2_b32 v[28:29], v10 offset0:16 offset1:49
	global_store_dwordx4 v[60:61], v[24:27], off nt
	v_lshlrev_b64 v[30:31], 12, v[30:31]
	v_lshl_add_u64 v[30:31], v[56:57], 0, v[30:31]
	s_waitcnt lgkmcnt(0)
	v_cvt_pk_bf16_f32 v24, v28, v29
	ds_read2_b32 v[26:27], v10 offset0:82 offset1:115
	s_waitcnt lgkmcnt(0)
	v_cvt_pk_bf16_f32 v25, v26, v27
	ds_read2_b32 v[26:27], v10 offset0:148 offset1:181
	s_waitcnt lgkmcnt(0)
	v_cvt_pk_bf16_f32 v26, v26, v27
	ds_read2_b32 v[28:29], v10 offset0:214 offset1:247
	s_waitcnt lgkmcnt(0)
	v_cvt_pk_bf16_f32 v27, v28, v29
	ds_read2_b32 v[28:29], v10 offset0:24 offset1:57
	global_store_dwordx4 v[62:63], v[24:27], off nt
	s_waitcnt lgkmcnt(0)
	s_nop 0
	v_cvt_pk_bf16_f32 v24, v28, v29
	ds_read2_b32 v[26:27], v10 offset0:90 offset1:123
	s_waitcnt lgkmcnt(0)
	v_cvt_pk_bf16_f32 v25, v26, v27
	ds_read2_b32 v[26:27], v10 offset0:156 offset1:189
	s_waitcnt lgkmcnt(0)
	v_cvt_pk_bf16_f32 v26, v26, v27
	ds_read2_b32 v[28:29], v10 offset0:222 offset1:255
	s_waitcnt lgkmcnt(0)
	v_cvt_pk_bf16_f32 v27, v28, v29
	global_store_dwordx4 v[30:31], v[24:27], off nt
	s_waitcnt lgkmcnt(0)
	s_cbranch_scc1 .LBB0_24

.LBB0_27:
	s_ashr_i32 s6, s12, 31
	s_lshr_b32 s6, s6, 25
	s_add_i32 s6, s12, s6
	s_ashr_i32 s6, s6, 7
	s_lshl_b32 s8, s6, 6
	s_lshl_b32 s7, s6, 12
	v_or_b32_e32 v24, s8, v1
	s_sub_i32 s6, s10, s7
	v_or_b32_e32 v26, 8, v24
	v_or_b32_e32 v28, 16, v24
	v_or_b32_e32 v30, 24, v24
	v_or_b32_e32 v32, 32, v24
	v_or_b32_e32 v34, 40, v24
	v_or_b32_e32 v36, 48, v24
	v_or_b32_e32 v38, 56, v24
	s_ashr_i32 s7, s6, 31
	v_ashrrev_i32_e32 v25, 31, v24
	v_ashrrev_i32_e32 v27, 31, v26
	v_ashrrev_i32_e32 v29, 31, v28
	v_ashrrev_i32_e32 v31, 31, v30
	v_ashrrev_i32_e32 v33, 31, v32
	v_ashrrev_i32_e32 v35, 31, v34
	v_ashrrev_i32_e32 v37, 31, v36
	v_ashrrev_i32_e32 v39, 31, v38
	v_lshl_add_u64 v[40:41], s[6:7], 2, v[6:7]
	v_lshlrev_b64 v[24:25], 14, v[24:25]
	v_lshlrev_b64 v[42:43], 14, v[26:27]
	v_lshlrev_b64 v[28:29], 14, v[28:29]
	v_lshlrev_b64 v[30:31], 14, v[30:31]
	v_lshlrev_b64 v[32:33], 14, v[32:33]
	v_lshlrev_b64 v[34:35], 14, v[34:35]
	v_lshlrev_b64 v[36:37], 14, v[36:37]
	v_lshlrev_b64 v[38:39], 14, v[38:39]
	v_lshl_add_u64 v[24:25], v[40:41], 0, v[24:25]
	v_lshl_add_u64 v[42:43], v[40:41], 0, v[42:43]
	v_lshl_add_u64 v[44:45], v[40:41], 0, v[28:29]
	v_lshl_add_u64 v[46:47], v[40:41], 0, v[30:31]
	v_lshl_add_u64 v[48:49], v[40:41], 0, v[32:33]
	v_lshl_add_u64 v[50:51], v[40:41], 0, v[34:35]
	v_lshl_add_u64 v[52:53], v[40:41], 0, v[36:37]
	v_lshl_add_u64 v[54:55], v[40:41], 0, v[38:39]
	global_load_dwordx4 v[24:27], v[24:25], off nt
	s_nop 0
	global_load_dwordx4 v[28:31], v[42:43], off nt
	global_load_dwordx4 v[32:35], v[44:45], off nt
	global_load_dwordx4 v[36:39], v[46:47], off nt
	s_nop 0
	global_load_dwordx4 v[40:43], v[48:49], off nt
	global_load_dwordx4 v[44:47], v[50:51], off nt
	s_nop 0
	global_load_dwordx4 v[48:51], v[52:53], off nt
	s_nop 0
	global_load_dwordx4 v[52:55], v[54:55], off nt
	v_add_u32_e32 v58, s6, v1
	s_ashr_i32 s9, s8, 31
	v_ashrrev_i32_e32 v59, 31, v58
	v_lshl_add_u64 v[56:57], s[8:9], 1, v[8:9]
	v_lshlrev_b64 v[64:65], 12, v[58:59]
	v_add_u32_e32 v60, 8, v58
	v_lshl_add_u64 v[64:65], v[56:57], 0, v[64:65]
	v_ashrrev_i32_e32 v61, 31, v60
	v_lshlrev_b64 v[60:61], 12, v[60:61]
	v_add_u32_e32 v62, 16, v58
	v_lshl_add_u64 v[60:61], v[56:57], 0, v[60:61]
	v_ashrrev_i32_e32 v63, 31, v62
	v_lshlrev_b64 v[62:63], 12, v[62:63]
	v_lshl_add_u64 v[62:63], v[56:57], 0, v[62:63]
	s_add_i32 s12, s12, s28
	s_add_i32 s10, s10, s11
	s_cmpk_lt_i32 s12, 0x1000
	s_waitcnt vmcnt(7)
	ds_write2_b32 v11, v24, v25 offset1:1
	ds_write2_b32 v11, v26, v27 offset0:2 offset1:3
	s_waitcnt vmcnt(6)
	ds_write2_b32 v3, v28, v29 offset1:1
	ds_write2_b32 v5, v30, v31 offset1:1
	s_waitcnt vmcnt(5)
	ds_write2_b32 v12, v32, v33 offset1:1
	ds_write2_b32 v13, v34, v35 offset1:1
	s_waitcnt vmcnt(4)
	ds_write2_b32 v14, v36, v37 offset1:1
	ds_write2_b32 v15, v38, v39 offset1:1
	s_waitcnt vmcnt(3)
	ds_write2_b32 v16, v40, v41 offset1:1
	ds_write2_b32 v17, v42, v43 offset1:1
	s_waitcnt vmcnt(2)
	ds_write2_b32 v18, v44, v45 offset1:1
	ds_write2_b32 v19, v46, v47 offset1:1
	s_waitcnt vmcnt(1)
	ds_write2_b32 v20, v48, v49 offset1:1
	ds_write2_b32 v21, v50, v51 offset1:1
	s_waitcnt vmcnt(0)
	ds_write2_b32 v22, v52, v53 offset1:1
	ds_write2_b32 v23, v54, v55 offset1:1
	s_waitcnt lgkmcnt(0)
	ds_read2_b32 v[24:25], v10 offset1:33
	s_waitcnt lgkmcnt(0)
	v_cvt_pk_bf16_f32 v24, v24, v25
	ds_read2_b32 v[26:27], v10 offset0:66 offset1:99
	s_waitcnt lgkmcnt(0)
	v_cvt_pk_bf16_f32 v25, v26, v27
	ds_read2_b32 v[26:27], v10 offset0:132 offset1:165
	s_waitcnt lgkmcnt(0)
	v_cvt_pk_bf16_f32 v26, v26, v27
	ds_read2_b32 v[28:29], v10 offset0:198 offset1:231
	s_waitcnt lgkmcnt(0)
	v_cvt_pk_bf16_f32 v27, v28, v29
	ds_read2_b32 v[28:29], v10 offset0:8 offset1:41
	global_store_dwordx4 v[64:65], v[24:27], off nt
	v_add_u32_e32 v30, 24, v58
	v_ashrrev_i32_e32 v31, 31, v30
	s_waitcnt lgkmcnt(0)
	v_cvt_pk_bf16_f32 v24, v28, v29
	ds_read2_b32 v[26:27], v10 offset0:74 offset1:107
	s_waitcnt lgkmcnt(0)
	v_cvt_pk_bf16_f32 v25, v26, v27
	ds_read2_b32 v[26:27], v10 offset0:140 offset1:173
	s_waitcnt lgkmcnt(0)
	v_cvt_pk_bf16_f32 v26, v26, v27
	ds_read2_b32 v[28:29], v10 offset0:206 offset1:239
	s_waitcnt lgkmcnt(0)
	v_cvt_pk_bf16_f32 v27, v28, v29
	ds_read2_b32 v[28:29], v10 offset0:16 offset1:49
	global_store_dwordx4 v[60:61], v[24:27], off nt
	v_lshlrev_b64 v[30:31], 12, v[30:31]
	v_lshl_add_u64 v[30:31], v[56:57], 0, v[30:31]
	s_waitcnt lgkmcnt(0)
	v_cvt_pk_bf16_f32 v24, v28, v29
	ds_read2_b32 v[26:27], v10 offset0:82 offset1:115
	s_waitcnt lgkmcnt(0)
	v_cvt_pk_bf16_f32 v25, v26, v27
	ds_read2_b32 v[26:27], v10 offset0:148 offset1:181
	s_waitcnt lgkmcnt(0)
	v_cvt_pk_bf16_f32 v26, v26, v27
	ds_read2_b32 v[28:29], v10 offset0:214 offset1:247
	s_waitcnt lgkmcnt(0)
	v_cvt_pk_bf16_f32 v27, v28, v29
	ds_read2_b32 v[28:29], v10 offset0:24 offset1:57
	global_store_dwordx4 v[62:63], v[24:27], off nt
	s_waitcnt lgkmcnt(0)
	s_nop 0
	v_cvt_pk_bf16_f32 v24, v28, v29
	ds_read2_b32 v[26:27], v10 offset0:90 offset1:123
	s_waitcnt lgkmcnt(0)
	v_cvt_pk_bf16_f32 v25, v26, v27
	ds_read2_b32 v[26:27], v10 offset0:156 offset1:189
	s_waitcnt lgkmcnt(0)
	v_cvt_pk_bf16_f32 v26, v26, v27
	ds_read2_b32 v[28:29], v10 offset0:222 offset1:255
	s_waitcnt lgkmcnt(0)
	v_cvt_pk_bf16_f32 v27, v28, v29
	global_store_dwordx4 v[30:31], v[24:27], off nt
	s_waitcnt lgkmcnt(0)
	s_cbranch_scc1 .LBB0_27

.LBB0_30:
	s_ashr_i32 s4, s10, 31
	s_lshr_b32 s4, s4, 26
	s_add_i32 s4, s10, s4
	s_lshl_b32 s5, s4, 5
	s_and_b32 s6, s4, 0xffffffc0
	s_and_b32 s4, s5, 0xfffff800
	v_or_b32_e32 v22, s6, v1
	s_sub_i32 s4, s8, s4
	v_or_b32_e32 v24, 8, v22
	v_or_b32_e32 v26, 16, v22
	v_or_b32_e32 v28, 24, v22
	v_or_b32_e32 v30, 32, v22
	v_or_b32_e32 v32, 40, v22
	v_or_b32_e32 v34, 48, v22
	v_or_b32_e32 v36, 56, v22
	v_ashrrev_i32_e32 v23, 31, v22
	s_ashr_i32 s5, s4, 31
	v_ashrrev_i32_e32 v25, 31, v24
	v_ashrrev_i32_e32 v27, 31, v26
	v_ashrrev_i32_e32 v29, 31, v28
	v_ashrrev_i32_e32 v31, 31, v30
	v_ashrrev_i32_e32 v33, 31, v32
	v_ashrrev_i32_e32 v35, 31, v34
	v_ashrrev_i32_e32 v37, 31, v36
	v_lshlrev_b64 v[22:23], 13, v[22:23]
	v_lshl_add_u64 v[38:39], s[4:5], 2, v[6:7]
	v_lshlrev_b64 v[24:25], 13, v[24:25]
	v_lshlrev_b64 v[26:27], 13, v[26:27]
	v_lshlrev_b64 v[28:29], 13, v[28:29]
	v_lshlrev_b64 v[30:31], 13, v[30:31]
	v_lshlrev_b64 v[32:33], 13, v[32:33]
	v_lshlrev_b64 v[34:35], 13, v[34:35]
	v_lshlrev_b64 v[36:37], 13, v[36:37]
	v_lshl_add_u64 v[22:23], v[38:39], 0, v[22:23]
	v_lshl_add_u64 v[40:41], v[38:39], 0, v[24:25]
	v_lshl_add_u64 v[42:43], v[38:39], 0, v[26:27]
	v_lshl_add_u64 v[44:45], v[38:39], 0, v[28:29]
	v_lshl_add_u64 v[46:47], v[38:39], 0, v[30:31]
	v_lshl_add_u64 v[48:49], v[38:39], 0, v[32:33]
	v_lshl_add_u64 v[50:51], v[38:39], 0, v[34:35]
	v_lshl_add_u64 v[52:53], v[38:39], 0, v[36:37]
	global_load_dwordx4 v[22:25], v[22:23], off nt
	s_nop 0
	global_load_dwordx4 v[26:29], v[40:41], off nt
	global_load_dwordx4 v[30:33], v[42:43], off nt
	global_load_dwordx4 v[34:37], v[44:45], off nt
	s_nop 0
	global_load_dwordx4 v[38:41], v[46:47], off nt
	global_load_dwordx4 v[42:45], v[48:49], off nt
	s_nop 0
	global_load_dwordx4 v[46:49], v[50:51], off nt
	s_nop 0
	global_load_dwordx4 v[50:53], v[52:53], off nt
	v_add_u32_e32 v56, s4, v1
	s_ashr_i32 s7, s6, 31
	v_ashrrev_i32_e32 v57, 31, v56
	v_lshl_add_u64 v[54:55], s[6:7], 1, v[2:3]
	v_lshlrev_b64 v[62:63], 12, v[56:57]
	v_add_u32_e32 v58, 8, v56
	v_lshl_add_u64 v[62:63], v[54:55], 0, v[62:63]
	v_ashrrev_i32_e32 v59, 31, v58
	v_lshlrev_b64 v[58:59], 12, v[58:59]
	v_add_u32_e32 v60, 16, v56
	v_lshl_add_u64 v[58:59], v[54:55], 0, v[58:59]
	v_ashrrev_i32_e32 v61, 31, v60
	v_lshlrev_b64 v[60:61], 12, v[60:61]
	v_lshl_add_u64 v[60:61], v[54:55], 0, v[60:61]
	s_add_i32 s10, s10, s28
	s_add_i32 s8, s8, s9
	s_cmpk_lt_i32 s10, 0x800
	s_waitcnt vmcnt(7)
	ds_write2_b32 v11, v22, v23 offset1:1
	ds_write2_b32 v11, v24, v25 offset0:2 offset1:3
	s_waitcnt vmcnt(6)
	ds_write2_b32 v4, v26, v27 offset1:1
	ds_write2_b32 v5, v28, v29 offset1:1
	s_waitcnt vmcnt(5)
	ds_write2_b32 v8, v30, v31 offset1:1
	ds_write2_b32 v9, v32, v33 offset1:1
	s_waitcnt vmcnt(4)
	ds_write2_b32 v12, v34, v35 offset1:1
	ds_write2_b32 v13, v36, v37 offset1:1
	s_waitcnt vmcnt(3)
	ds_write2_b32 v14, v38, v39 offset1:1
	ds_write2_b32 v15, v40, v41 offset1:1
	s_waitcnt vmcnt(2)
	ds_write2_b32 v16, v42, v43 offset1:1
	ds_write2_b32 v17, v44, v45 offset1:1
	s_waitcnt vmcnt(1)
	ds_write2_b32 v18, v46, v47 offset1:1
	ds_write2_b32 v19, v48, v49 offset1:1
	s_waitcnt vmcnt(0)
	ds_write2_b32 v20, v50, v51 offset1:1
	ds_write2_b32 v21, v52, v53 offset1:1
	s_waitcnt lgkmcnt(0)
	ds_read2_b32 v[22:23], v10 offset1:33
	s_waitcnt lgkmcnt(0)
	v_cvt_pk_bf16_f32 v22, v22, v23
	ds_read2_b32 v[24:25], v10 offset0:66 offset1:99
	s_waitcnt lgkmcnt(0)
	v_cvt_pk_bf16_f32 v23, v24, v25
	ds_read2_b32 v[24:25], v10 offset0:132 offset1:165
	s_waitcnt lgkmcnt(0)
	v_cvt_pk_bf16_f32 v24, v24, v25
	ds_read2_b32 v[26:27], v10 offset0:198 offset1:231
	s_waitcnt lgkmcnt(0)
	v_cvt_pk_bf16_f32 v25, v26, v27
	ds_read2_b32 v[26:27], v10 offset0:8 offset1:41
	global_store_dwordx4 v[62:63], v[22:25], off nt
	v_add_u32_e32 v28, 24, v56
	v_ashrrev_i32_e32 v29, 31, v28
	s_waitcnt lgkmcnt(0)
	v_cvt_pk_bf16_f32 v22, v26, v27
	ds_read2_b32 v[24:25], v10 offset0:74 offset1:107
	s_waitcnt lgkmcnt(0)
	v_cvt_pk_bf16_f32 v23, v24, v25
	ds_read2_b32 v[24:25], v10 offset0:140 offset1:173
	s_waitcnt lgkmcnt(0)
	v_cvt_pk_bf16_f32 v24, v24, v25
	ds_read2_b32 v[26:27], v10 offset0:206 offset1:239
	s_waitcnt lgkmcnt(0)
	v_cvt_pk_bf16_f32 v25, v26, v27
	ds_read2_b32 v[26:27], v10 offset0:16 offset1:49
	global_store_dwordx4 v[58:59], v[22:25], off nt
	v_lshlrev_b64 v[28:29], 12, v[28:29]
	v_lshl_add_u64 v[28:29], v[54:55], 0, v[28:29]
	s_waitcnt lgkmcnt(0)
	v_cvt_pk_bf16_f32 v22, v26, v27
	ds_read2_b32 v[24:25], v10 offset0:82 offset1:115
	s_waitcnt lgkmcnt(0)
	v_cvt_pk_bf16_f32 v23, v24, v25
	ds_read2_b32 v[24:25], v10 offset0:148 offset1:181
	s_waitcnt lgkmcnt(0)
	v_cvt_pk_bf16_f32 v24, v24, v25
	ds_read2_b32 v[26:27], v10 offset0:214 offset1:247
	s_waitcnt lgkmcnt(0)
	v_cvt_pk_bf16_f32 v25, v26, v27
	ds_read2_b32 v[26:27], v10 offset0:24 offset1:57
	global_store_dwordx4 v[60:61], v[22:25], off nt
	s_waitcnt lgkmcnt(0)
	s_nop 0
	v_cvt_pk_bf16_f32 v22, v26, v27
	ds_read2_b32 v[24:25], v10 offset0:90 offset1:123
	s_waitcnt lgkmcnt(0)
	v_cvt_pk_bf16_f32 v23, v24, v25
	ds_read2_b32 v[24:25], v10 offset0:156 offset1:189
	s_waitcnt lgkmcnt(0)
	v_cvt_pk_bf16_f32 v24, v24, v25
	ds_read2_b32 v[26:27], v10 offset0:222 offset1:255
	s_waitcnt lgkmcnt(0)
	v_cvt_pk_bf16_f32 v25, v26, v27
	global_store_dwordx4 v[28:29], v[22:25], off nt
	s_waitcnt lgkmcnt(0)
	s_cbranch_scc1 .LBB0_30
